# P9 epilogue second half: pairs of 64-byte half-line out stores -> whole-line stores (8 rows x 128 B per instruction) via DPP row_ror:8
# speedup vs baseline: 1.0015x; 1.0015x over previous
;     __device__ __forceinline__ void fused(f32x4 (&acc)[2][2][4][2], const Unit& u, int wr, int wc, int fr, int fq, PG8_LAS unsigned char* lds, int wid, int lane) const {
;     ...
; #pragma unroll
;         for (int ai = 0; ai < 2; ++ai)
; #pragma unroll
;             for (int m = 0; m < 4; ++m) { const int r = ai * HALF + wr * 64 + m * 16 + fr; const f32x2v sr = S[r]; const size_t off = (size_t)(u.pm * BM + r) * ldc + col0;
; #pragma unroll
;                 for (int bj = 0; bj < 2; ++bj)
; #pragma unroll
;                     for (int n = 0; n < 2; ++n) { const f32x4 bs = ai == 0 ? pre[m][bj][n] : *(const f32x4*)(base + off + bj * HALF + n * 16); f32x4 o = bs + cvv[bj][n] * (acc[ai][bj][m][n] * sr.y);
;                         if (bad) o = (f32x4){qnan, qnan, qnan, qnan}; *(f32x4*)(out + off + bj * HALF + n * 16) = o; }
.LBB0_1304:
	s_or_b64 exec, exec, s[2:3]
	v_lshl_add_u32 v0, v219, 3, 0
	s_waitcnt lgkmcnt(0)
	s_barrier
	v_add_u32_e32 v216, 0x2000, v0
	ds_read2_b64 v[220:223], v216 offset1:16
	s_waitcnt vmcnt(0) lgkmcnt(0)
	v_or_b32_e32 v217, v217, v218
	v_add_u32_e32 v0, s16, v219
	v_ashrrev_i32_e32 v1, 31, v0
	v_cmp_ne_u32_e32 vcc, 0, v217
	v_pk_mul_f32 v[128:129], v[128:129], v[220:221] op_sel:[0,1]
	v_pk_mul_f32 v[126:127], v[126:127], v[220:221] op_sel:[0,1]
	v_pk_fma_f32 v[128:129], v[144:145], v[128:129], v[208:209]
	v_pk_fma_f32 v[206:207], v[142:143], v[126:127], v[206:207]
	v_mov_b32_e32 v126, 0x7fc00000
	v_cndmask_b32_e32 v209, v129, v126, vcc
	v_cndmask_b32_e32 v208, v128, v126, vcc
	v_lshlrev_b64 v[128:129], 12, v[0:1]
	v_pk_mul_f32 v[120:121], v[120:121], v[220:221] op_sel:[0,1]
	v_pk_mul_f32 v[118:119], v[118:119], v[220:221] op_sel:[0,1]
	v_pk_mul_f32 v[112:113], v[112:113], v[220:221] op_sel:[0,1]
	v_pk_mul_f32 v[110:111], v[110:111], v[220:221] op_sel:[0,1]
	v_lshl_add_u64 v[128:129], s[76:77], 0, v[128:129]
	v_pk_fma_f32 v[118:119], v[134:135], v[118:119], v[198:199]
	v_pk_fma_f32 v[120:121], v[136:137], v[120:121], v[200:201]
	v_pk_fma_f32 v[110:111], v[130:131], v[110:111], v[194:195]
	v_pk_fma_f32 v[112:113], v[132:133], v[112:113], v[196:197]
	v_lshl_add_u64 v[128:129], v[128:129], 0, v[214:215]
	v_cndmask_b32_e32 v121, v121, v126, vcc
	v_cndmask_b32_e32 v120, v120, v126, vcc
	v_cndmask_b32_e32 v119, v119, v126, vcc
	v_cndmask_b32_e32 v118, v118, v126, vcc
	v_cndmask_b32_e32 v113, v113, v126, vcc
	v_cndmask_b32_e32 v112, v112, v126, vcc
	v_cndmask_b32_e32 v111, v111, v126, vcc
	v_cndmask_b32_e32 v110, v110, v126, vcc
	global_store_dwordx4 v[128:129], v[118:121], off offset:512 sc1
	global_store_dwordx4 v[128:129], v[110:113], off offset:576 sc1
	v_pk_mul_f32 v[124:125], v[124:125], v[220:221] op_sel:[0,1]
	v_add_u32_e32 v118, 16, v0
	v_pk_mul_f32 v[110:111], v[116:117], v[222:223] op_sel:[0,1]
	v_pk_mul_f32 v[112:113], v[114:115], v[222:223] op_sel:[0,1]
	v_ashrrev_i32_e32 v119, 31, v118
	v_pk_fma_f32 v[114:115], v[142:143], v[112:113], v[190:191]
	v_pk_fma_f32 v[110:111], v[144:145], v[110:111], v[192:193]
	v_pk_mul_f32 v[122:123], v[122:123], v[220:221] op_sel:[0,1]
	v_cndmask_b32_e32 v113, v111, v126, vcc
	v_cndmask_b32_e32 v112, v110, v126, vcc
	v_cndmask_b32_e32 v111, v115, v126, vcc
	v_cndmask_b32_e32 v110, v114, v126, vcc
	v_lshlrev_b64 v[114:115], 12, v[118:119]
	v_pk_mul_f32 v[108:109], v[108:109], v[222:223] op_sel:[0,1]
	v_pk_mul_f32 v[106:107], v[106:107], v[222:223] op_sel:[0,1]
	v_pk_mul_f32 v[104:105], v[104:105], v[222:223] op_sel:[0,1]
	v_pk_mul_f32 v[102:103], v[102:103], v[222:223] op_sel:[0,1]
	v_pk_mul_f32 v[96:97], v[96:97], v[222:223] op_sel:[0,1]
	v_pk_mul_f32 v[94:95], v[94:95], v[222:223] op_sel:[0,1]
	v_pk_fma_f32 v[122:123], v[138:139], v[122:123], v[202:203]
	v_pk_fma_f32 v[124:125], v[140:141], v[124:125], v[204:205]
	v_lshl_add_u64 v[114:115], s[76:77], 0, v[114:115]
	v_pk_fma_f32 v[106:107], v[138:139], v[106:107], v[186:187]
	v_pk_fma_f32 v[108:109], v[140:141], v[108:109], v[188:189]
	v_pk_fma_f32 v[102:103], v[134:135], v[102:103], v[182:183]
	v_pk_fma_f32 v[104:105], v[136:137], v[104:105], v[184:185]
	v_pk_fma_f32 v[94:95], v[130:131], v[94:95], v[178:179]
	v_pk_fma_f32 v[96:97], v[132:133], v[96:97], v[180:181]
	v_cndmask_b32_e32 v207, v207, v126, vcc
	v_cndmask_b32_e32 v206, v206, v126, vcc
	v_cndmask_b32_e32 v125, v125, v126, vcc
	v_cndmask_b32_e32 v124, v124, v126, vcc
	v_cndmask_b32_e32 v123, v123, v126, vcc
	v_cndmask_b32_e32 v122, v122, v126, vcc
	v_lshl_add_u64 v[114:115], v[114:115], 0, v[214:215]
	v_cndmask_b32_e32 v109, v109, v126, vcc
	v_cndmask_b32_e32 v108, v108, v126, vcc
	v_cndmask_b32_e32 v107, v107, v126, vcc
	v_cndmask_b32_e32 v106, v106, v126, vcc
	v_cndmask_b32_e32 v105, v105, v126, vcc
	v_cndmask_b32_e32 v104, v104, v126, vcc
	v_cndmask_b32_e32 v103, v103, v126, vcc
	v_cndmask_b32_e32 v102, v102, v126, vcc
	v_cndmask_b32_e32 v97, v97, v126, vcc
	v_cndmask_b32_e32 v96, v96, v126, vcc
	v_cndmask_b32_e32 v95, v95, v126, vcc
	v_cndmask_b32_e32 v94, v94, v126, vcc
	global_store_dwordx4 v[128:129], v[206:209], off sc1
	global_store_dwordx4 v[128:129], v[122:125], off offset:64 sc1
	global_store_dwordx4 v[114:115], v[110:113], off sc1
	global_store_dwordx4 v[114:115], v[106:109], off offset:64 sc1
	global_store_dwordx4 v[114:115], v[102:105], off offset:512 sc1
	global_store_dwordx4 v[114:115], v[94:97], off offset:576 sc1
	ds_read2_b64 v[94:97], v216 offset0:32 offset1:48
	v_add_u32_e32 v102, 32, v0
	v_ashrrev_i32_e32 v103, 31, v102
	v_lshlrev_b64 v[102:103], 12, v[102:103]
	v_lshl_add_u64 v[102:103], s[76:77], 0, v[102:103]
	s_waitcnt lgkmcnt(0)
;     __device__ __forceinline__ void fused(f32x4 (&acc)[2][2][4][2], const Unit& u, int wr, int wc, int fr, int fq, PG8_LAS unsigned char* lds, int wid, int lane) const {
;     ...
;             for (int m = 0; m < 4; ++m) { const int r = ai * HALF + wr * 64 + m * 16 + fr; const f32x2v sr = S[r]; const size_t off = (size_t)(u.pm * BM + r) * ldc + col0;
; #pragma unroll
;                 for (int bj = 0; bj < 2; ++bj)
; #pragma unroll
;                     for (int n = 0; n < 2; ++n) { const f32x4 bs = ai == 0 ? pre[m][bj][n] : *(const f32x4*)(base + off + bj * HALF + n * 16); f32x4 o = bs + cvv[bj][n] * (acc[ai][bj][m][n] * sr.y);
;                         if (bad) o = (f32x4){qnan, qnan, qnan, qnan}; *(f32x4*)(out + off + bj * HALF + n * 16) = o; }
	v_pk_mul_f32 v[88:89], v[88:89], v[94:95] op_sel:[0,1]
	v_pk_mul_f32 v[86:87], v[86:87], v[94:95] op_sel:[0,1]
	v_pk_mul_f32 v[80:81], v[80:81], v[94:95] op_sel:[0,1]
	v_pk_mul_f32 v[78:79], v[78:79], v[94:95] op_sel:[0,1]
	v_pk_fma_f32 v[86:87], v[134:135], v[86:87], v[166:167]
	v_pk_fma_f32 v[88:89], v[136:137], v[88:89], v[168:169]
	v_pk_fma_f32 v[78:79], v[130:131], v[78:79], v[162:163]
	v_pk_fma_f32 v[80:81], v[132:133], v[80:81], v[164:165]
	v_lshl_add_u64 v[102:103], v[102:103], 0, v[214:215]
	v_cndmask_b32_e32 v89, v89, v126, vcc
	v_cndmask_b32_e32 v88, v88, v126, vcc
	v_cndmask_b32_e32 v87, v87, v126, vcc
	v_cndmask_b32_e32 v86, v86, v126, vcc
	v_cndmask_b32_e32 v81, v81, v126, vcc
	v_cndmask_b32_e32 v80, v80, v126, vcc
	v_cndmask_b32_e32 v79, v79, v126, vcc
	v_cndmask_b32_e32 v78, v78, v126, vcc
	global_store_dwordx4 v[102:103], v[86:89], off offset:512 sc1
	global_store_dwordx4 v[102:103], v[78:81], off offset:576 sc1
	v_pk_mul_f32 v[76:77], v[76:77], v[96:97] op_sel:[0,1]
	v_add_u32_e32 v86, 48, v0
	v_pk_mul_f32 v[78:79], v[84:85], v[96:97] op_sel:[0,1]
	v_pk_mul_f32 v[80:81], v[82:83], v[96:97] op_sel:[0,1]
	v_ashrrev_i32_e32 v87, 31, v86
	v_pk_fma_f32 v[82:83], v[142:143], v[80:81], v[158:159]
	v_pk_fma_f32 v[78:79], v[144:145], v[78:79], v[160:161]
	v_pk_mul_f32 v[74:75], v[74:75], v[96:97] op_sel:[0,1]
	v_cndmask_b32_e32 v81, v79, v126, vcc
	v_cndmask_b32_e32 v80, v78, v126, vcc
	v_cndmask_b32_e32 v79, v83, v126, vcc
	v_cndmask_b32_e32 v78, v82, v126, vcc
	v_lshlrev_b64 v[82:83], 12, v[86:87]
	v_lshl_add_u64 v[82:83], s[76:77], 0, v[82:83]
	v_pk_fma_f32 v[74:75], v[138:139], v[74:75], v[154:155]
	v_pk_fma_f32 v[76:77], v[140:141], v[76:77], v[156:157]
	v_pk_mul_f32 v[100:101], v[100:101], v[94:95] op_sel:[0,1]
	v_pk_mul_f32 v[98:99], v[98:99], v[94:95] op_sel:[0,1]
	v_pk_mul_f32 v[92:93], v[92:93], v[94:95] op_sel:[0,1]
	v_pk_mul_f32 v[90:91], v[90:91], v[94:95] op_sel:[0,1]
	v_lshl_add_u64 v[82:83], v[82:83], 0, v[214:215]
	v_cndmask_b32_e32 v77, v77, v126, vcc
	v_cndmask_b32_e32 v76, v76, v126, vcc
	v_cndmask_b32_e32 v75, v75, v126, vcc
	v_cndmask_b32_e32 v74, v74, v126, vcc
	v_pk_mul_f32 v[72:73], v[72:73], v[96:97] op_sel:[0,1]
	v_pk_mul_f32 v[70:71], v[70:71], v[96:97] op_sel:[0,1]
	v_pk_mul_f32 v[68:69], v[68:69], v[96:97] op_sel:[0,1]
	v_pk_mul_f32 v[66:67], v[66:67], v[96:97] op_sel:[0,1]
	v_pk_fma_f32 v[98:99], v[142:143], v[98:99], v[174:175]
	v_pk_fma_f32 v[100:101], v[144:145], v[100:101], v[176:177]
	v_pk_fma_f32 v[90:91], v[138:139], v[90:91], v[170:171]
	v_pk_fma_f32 v[92:93], v[140:141], v[92:93], v[172:173]
	global_store_dwordx4 v[82:83], v[74:77], off offset:64 sc1
	v_pk_fma_f32 v[70:71], v[134:135], v[70:71], v[150:151]
	v_pk_fma_f32 v[72:73], v[136:137], v[72:73], v[152:153]
	v_pk_fma_f32 v[66:67], v[130:131], v[66:67], v[146:147]
	v_pk_fma_f32 v[68:69], v[132:133], v[68:69], v[148:149]
	v_add_u32_e32 v74, 0x80, v0
	v_cndmask_b32_e32 v101, v101, v126, vcc
	v_cndmask_b32_e32 v100, v100, v126, vcc
	v_cndmask_b32_e32 v99, v99, v126, vcc
	v_cndmask_b32_e32 v98, v98, v126, vcc
	v_cndmask_b32_e32 v93, v93, v126, vcc
	v_cndmask_b32_e32 v92, v92, v126, vcc
	v_cndmask_b32_e32 v91, v91, v126, vcc
	v_cndmask_b32_e32 v90, v90, v126, vcc
	v_cndmask_b32_e32 v73, v73, v126, vcc
	v_cndmask_b32_e32 v72, v72, v126, vcc
	v_cndmask_b32_e32 v71, v71, v126, vcc
	v_cndmask_b32_e32 v70, v70, v126, vcc
	v_cndmask_b32_e32 v69, v69, v126, vcc
	v_cndmask_b32_e32 v68, v68, v126, vcc
	v_cndmask_b32_e32 v67, v67, v126, vcc
	v_cndmask_b32_e32 v66, v66, v126, vcc
	v_ashrrev_i32_e32 v75, 31, v74
	global_store_dwordx4 v[102:103], v[98:101], off sc1
	global_store_dwordx4 v[102:103], v[90:93], off offset:64 sc1
	global_store_dwordx4 v[82:83], v[78:81], off sc1
	global_store_dwordx4 v[82:83], v[70:73], off offset:512 sc1
	global_store_dwordx4 v[82:83], v[66:69], off offset:576 sc1
	ds_read2_b64 v[88:91], v216 offset0:128 offset1:144
	s_mov_b32 s98, 0xff00ff
	s_mov_b32 s99, 0xff00ff
	s_mov_b32 s100, 0x8000
	s_mov_b32 s101, 0
	v_mbcnt_lo_u32_b32 v254, -1, 0
	v_mbcnt_hi_u32_b32 v254, -1, v254
	v_bfe_u32 v254, v254, 3, 1
	v_sub_u32_e32 v255, 0, v254
	v_and_b32_e32 v254, 0xffff8040, v255
	ds_read2_b64 v[92:95], v216 offset0:160 offset1:176
	v_mov_b32_e32 v86, 0x10000
	v_mov_b32_e32 v87, 0
	v_add_u32_e32 v66, 0x80, v0
	v_ashrrev_i32_e32 v67, 31, v66
	v_lshlrev_b64 v[68:69], 12, v[66:67]
	v_lshl_add_u64 v[70:71], v[212:213], 0, v[68:69]
	v_lshl_add_u64 v[72:73], s[76:77], 0, v[68:69]
	v_lshl_add_u64 v[72:73], v[72:73], 0, v[214:215]
	global_load_dwordx4 v[146:149], v[70:71], off nt
	global_load_dwordx4 v[150:153], v[70:71], off offset:64 nt
	global_load_dwordx4 v[154:157], v[70:71], off offset:512 nt
	global_load_dwordx4 v[158:161], v[70:71], off offset:576 nt
	v_lshl_add_u64 v[74:75], v[70:71], 0, v[86:87]
	v_lshl_add_u64 v[76:77], v[72:73], 0, v[86:87]
	global_load_dwordx4 v[162:165], v[74:75], off nt
	global_load_dwordx4 v[166:169], v[74:75], off offset:64 nt
	global_load_dwordx4 v[170:173], v[74:75], off offset:512 nt
	global_load_dwordx4 v[174:177], v[74:75], off offset:576 nt
	v_lshl_add_u64 v[78:79], v[74:75], 0, v[86:87]
	v_lshl_add_u64 v[80:81], v[76:77], 0, v[86:87]
	global_load_dwordx4 v[178:181], v[78:79], off nt
	global_load_dwordx4 v[182:185], v[78:79], off offset:64 nt
	global_load_dwordx4 v[186:189], v[78:79], off offset:512 nt
	global_load_dwordx4 v[190:193], v[78:79], off offset:576 nt
	v_lshl_add_u64 v[82:83], v[78:79], 0, v[86:87]
	v_lshl_add_u64 v[84:85], v[80:81], 0, v[86:87]
	global_load_dwordx4 v[194:197], v[82:83], off nt
	global_load_dwordx4 v[198:201], v[82:83], off offset:64 nt
	global_load_dwordx4 v[202:205], v[82:83], off offset:512 nt
	global_load_dwordx4 v[206:209], v[82:83], off offset:576 nt
	s_waitcnt lgkmcnt(0)
;     __device__ __forceinline__ void fused(f32x4 (&acc)[2][2][4][2], const Unit& u, int wr, int wc, int fr, int fq, PG8_LAS unsigned char* lds, int wid, int lane) const {
;     ...
;             for (int m = 0; m < 4; ++m) { const int r = ai * HALF + wr * 64 + m * 16 + fr; const f32x2v sr = S[r]; const size_t off = (size_t)(u.pm * BM + r) * ldc + col0;
; #pragma unroll
;                 for (int bj = 0; bj < 2; ++bj)
; #pragma unroll
;                     for (int n = 0; n < 2; ++n) { const f32x4 bs = ai == 0 ? pre[m][bj][n] : *(const f32x4*)(base + off + bj * HALF + n * 16); f32x4 o = bs + cvv[bj][n] * (acc[ai][bj][m][n] * sr.y);
;                         if (bad) o = (f32x4){qnan, qnan, qnan, qnan}; *(f32x4*)(out + off + bj * HALF + n * 16) = o; }
;                 if (m & 1) asm volatile("" ::: "memory"); }
	v_pk_mul_f32 v[62:63], v[62:63], v[88:89] op_sel:[0,1]
	v_pk_mul_f32 v[64:65], v[64:65], v[88:89] op_sel:[0,1]
	v_pk_mul_f32 v[58:59], v[58:59], v[88:89] op_sel:[0,1]
	v_pk_mul_f32 v[60:61], v[60:61], v[88:89] op_sel:[0,1]
	v_pk_mul_f32 v[54:55], v[54:55], v[88:89] op_sel:[0,1]
	v_pk_mul_f32 v[56:57], v[56:57], v[88:89] op_sel:[0,1]
	v_pk_mul_f32 v[46:47], v[46:47], v[88:89] op_sel:[0,1]
	v_pk_mul_f32 v[48:49], v[48:49], v[88:89] op_sel:[0,1]
	s_waitcnt vmcnt(15)
	v_pk_fma_f32 v[62:63], v[142:143], v[62:63], v[146:147]
	v_pk_fma_f32 v[64:65], v[144:145], v[64:65], v[148:149]
	v_cndmask_b32_e32 v62, v62, v126, vcc
	v_cndmask_b32_e32 v63, v63, v126, vcc
	v_cndmask_b32_e32 v64, v64, v126, vcc
	v_cndmask_b32_e32 v65, v65, v126, vcc
	s_waitcnt vmcnt(14)
	v_pk_fma_f32 v[58:59], v[138:139], v[58:59], v[150:151]
	v_pk_fma_f32 v[60:61], v[140:141], v[60:61], v[152:153]
	v_cndmask_b32_e32 v58, v58, v126, vcc
	v_cndmask_b32_e32 v59, v59, v126, vcc
	v_cndmask_b32_e32 v60, v60, v126, vcc
	v_cndmask_b32_e32 v61, v61, v126, vcc
	s_nop 1
	v_mov_b32_dpp v146, v62 row_ror:8 row_mask:0xf bank_mask:0xf
	v_mov_b32_dpp v147, v63 row_ror:8 row_mask:0xf bank_mask:0xf
	v_mov_b32_dpp v148, v64 row_ror:8 row_mask:0xf bank_mask:0xf
	v_mov_b32_dpp v149, v65 row_ror:8 row_mask:0xf bank_mask:0xf
	v_mov_b32_dpp v150, v58 row_ror:8 row_mask:0xf bank_mask:0xf
	v_mov_b32_dpp v151, v59 row_ror:8 row_mask:0xf bank_mask:0xf
	v_mov_b32_dpp v152, v60 row_ror:8 row_mask:0xf bank_mask:0xf
	v_mov_b32_dpp v153, v61 row_ror:8 row_mask:0xf bank_mask:0xf
	v_lshl_add_u64 v[250:251], v[72:73], 0, v[254:255]
	v_cndmask_b32_e64 v242, v150, v62, s[98:99]
	v_cndmask_b32_e64 v243, v151, v63, s[98:99]
	v_cndmask_b32_e64 v244, v152, v64, s[98:99]
	v_cndmask_b32_e64 v245, v153, v65, s[98:99]
	v_cndmask_b32_e64 v246, v58, v146, s[98:99]
	v_cndmask_b32_e64 v247, v59, v147, s[98:99]
	v_cndmask_b32_e64 v248, v60, v148, s[98:99]
	v_cndmask_b32_e64 v249, v61, v149, s[98:99]
	v_lshl_add_u64 v[252:253], v[250:251], 0, s[100:101]
	global_store_dwordx4 v[250:251], v[242:245], off sc1
	global_store_dwordx4 v[252:253], v[246:249], off sc1
	s_waitcnt vmcnt(15)
	v_pk_fma_f32 v[54:55], v[134:135], v[54:55], v[154:155]
	v_pk_fma_f32 v[56:57], v[136:137], v[56:57], v[156:157]
	v_cndmask_b32_e32 v54, v54, v126, vcc
	v_cndmask_b32_e32 v55, v55, v126, vcc
	v_cndmask_b32_e32 v56, v56, v126, vcc
	v_cndmask_b32_e32 v57, v57, v126, vcc
	s_waitcnt vmcnt(14)
	v_pk_fma_f32 v[46:47], v[130:131], v[46:47], v[158:159]
	v_pk_fma_f32 v[48:49], v[132:133], v[48:49], v[160:161]
	v_cndmask_b32_e32 v46, v46, v126, vcc
	v_cndmask_b32_e32 v47, v47, v126, vcc
	v_cndmask_b32_e32 v48, v48, v126, vcc
	v_cndmask_b32_e32 v49, v49, v126, vcc
	s_nop 1
	v_mov_b32_dpp v154, v54 row_ror:8 row_mask:0xf bank_mask:0xf
	v_mov_b32_dpp v155, v55 row_ror:8 row_mask:0xf bank_mask:0xf
	v_mov_b32_dpp v156, v56 row_ror:8 row_mask:0xf bank_mask:0xf
	v_mov_b32_dpp v157, v57 row_ror:8 row_mask:0xf bank_mask:0xf
	v_mov_b32_dpp v158, v46 row_ror:8 row_mask:0xf bank_mask:0xf
	v_mov_b32_dpp v159, v47 row_ror:8 row_mask:0xf bank_mask:0xf
	v_mov_b32_dpp v160, v48 row_ror:8 row_mask:0xf bank_mask:0xf
	v_mov_b32_dpp v161, v49 row_ror:8 row_mask:0xf bank_mask:0xf
	v_lshl_add_u64 v[250:251], v[72:73], 0, v[254:255]
	v_cndmask_b32_e64 v242, v158, v54, s[98:99]
	v_cndmask_b32_e64 v243, v159, v55, s[98:99]
	v_cndmask_b32_e64 v244, v160, v56, s[98:99]
	v_cndmask_b32_e64 v245, v161, v57, s[98:99]
	v_cndmask_b32_e64 v246, v46, v154, s[98:99]
	v_cndmask_b32_e64 v247, v47, v155, s[98:99]
	v_cndmask_b32_e64 v248, v48, v156, s[98:99]
	v_cndmask_b32_e64 v249, v49, v157, s[98:99]
	v_lshl_add_u64 v[252:253], v[250:251], 0, s[100:101]
	global_store_dwordx4 v[250:251], v[242:245], off offset:512 sc1
	global_store_dwordx4 v[252:253], v[246:249], off offset:512 sc1
	v_pk_mul_f32 v[50:51], v[50:51], v[90:91] op_sel:[0,1]
	v_pk_mul_f32 v[52:53], v[52:53], v[90:91] op_sel:[0,1]
	v_pk_mul_f32 v[42:43], v[42:43], v[90:91] op_sel:[0,1]
	v_pk_mul_f32 v[44:45], v[44:45], v[90:91] op_sel:[0,1]
	v_pk_mul_f32 v[38:39], v[38:39], v[90:91] op_sel:[0,1]
	v_pk_mul_f32 v[40:41], v[40:41], v[90:91] op_sel:[0,1]
	v_pk_mul_f32 v[30:31], v[30:31], v[90:91] op_sel:[0,1]
	v_pk_mul_f32 v[32:33], v[32:33], v[90:91] op_sel:[0,1]
	s_waitcnt vmcnt(15)
	v_pk_fma_f32 v[50:51], v[142:143], v[50:51], v[162:163]
	v_pk_fma_f32 v[52:53], v[144:145], v[52:53], v[164:165]
	v_cndmask_b32_e32 v50, v50, v126, vcc
	v_cndmask_b32_e32 v51, v51, v126, vcc
	v_cndmask_b32_e32 v52, v52, v126, vcc
	v_cndmask_b32_e32 v53, v53, v126, vcc
	s_waitcnt vmcnt(14)
	v_pk_fma_f32 v[42:43], v[138:139], v[42:43], v[166:167]
	v_pk_fma_f32 v[44:45], v[140:141], v[44:45], v[168:169]
	v_cndmask_b32_e32 v42, v42, v126, vcc
	v_cndmask_b32_e32 v43, v43, v126, vcc
	v_cndmask_b32_e32 v44, v44, v126, vcc
	v_cndmask_b32_e32 v45, v45, v126, vcc
	s_nop 1
	v_mov_b32_dpp v162, v50 row_ror:8 row_mask:0xf bank_mask:0xf
	v_mov_b32_dpp v163, v51 row_ror:8 row_mask:0xf bank_mask:0xf
	v_mov_b32_dpp v164, v52 row_ror:8 row_mask:0xf bank_mask:0xf
	v_mov_b32_dpp v165, v53 row_ror:8 row_mask:0xf bank_mask:0xf
	v_mov_b32_dpp v166, v42 row_ror:8 row_mask:0xf bank_mask:0xf
	v_mov_b32_dpp v167, v43 row_ror:8 row_mask:0xf bank_mask:0xf
	v_mov_b32_dpp v168, v44 row_ror:8 row_mask:0xf bank_mask:0xf
	v_mov_b32_dpp v169, v45 row_ror:8 row_mask:0xf bank_mask:0xf
	v_lshl_add_u64 v[250:251], v[76:77], 0, v[254:255]
	v_cndmask_b32_e64 v242, v166, v50, s[98:99]
	v_cndmask_b32_e64 v243, v167, v51, s[98:99]
	v_cndmask_b32_e64 v244, v168, v52, s[98:99]
	v_cndmask_b32_e64 v245, v169, v53, s[98:99]
	v_cndmask_b32_e64 v246, v42, v162, s[98:99]
	v_cndmask_b32_e64 v247, v43, v163, s[98:99]
	v_cndmask_b32_e64 v248, v44, v164, s[98:99]
	v_cndmask_b32_e64 v249, v45, v165, s[98:99]
	v_lshl_add_u64 v[252:253], v[250:251], 0, s[100:101]
	global_store_dwordx4 v[250:251], v[242:245], off sc1
	global_store_dwordx4 v[252:253], v[246:249], off sc1
	s_waitcnt vmcnt(15)
;     __device__ __forceinline__ void fused(f32x4 (&acc)[2][2][4][2], const Unit& u, int wr, int wc, int fr, int fq, PG8_LAS unsigned char* lds, int wid, int lane) const {
;     ...
;             for (int m = 0; m < 4; ++m) { const int r = ai * HALF + wr * 64 + m * 16 + fr; const f32x2v sr = S[r]; const size_t off = (size_t)(u.pm * BM + r) * ldc + col0;
; #pragma unroll
;                 for (int bj = 0; bj < 2; ++bj)
; #pragma unroll
;                     for (int n = 0; n < 2; ++n) { const f32x4 bs = ai == 0 ? pre[m][bj][n] : *(const f32x4*)(base + off + bj * HALF + n * 16); f32x4 o = bs + cvv[bj][n] * (acc[ai][bj][m][n] * sr.y);
;                         if (bad) o = (f32x4){qnan, qnan, qnan, qnan}; *(f32x4*)(out + off + bj * HALF + n * 16) = o; }
;                 if (m & 1) asm volatile("" ::: "memory"); }
	v_pk_fma_f32 v[38:39], v[134:135], v[38:39], v[170:171]
	v_pk_fma_f32 v[40:41], v[136:137], v[40:41], v[172:173]
	v_cndmask_b32_e32 v38, v38, v126, vcc
	v_cndmask_b32_e32 v39, v39, v126, vcc
	v_cndmask_b32_e32 v40, v40, v126, vcc
	v_cndmask_b32_e32 v41, v41, v126, vcc
	s_waitcnt vmcnt(14)
	v_pk_fma_f32 v[30:31], v[130:131], v[30:31], v[174:175]
	v_pk_fma_f32 v[32:33], v[132:133], v[32:33], v[176:177]
	v_cndmask_b32_e32 v30, v30, v126, vcc
	v_cndmask_b32_e32 v31, v31, v126, vcc
	v_cndmask_b32_e32 v32, v32, v126, vcc
	v_cndmask_b32_e32 v33, v33, v126, vcc
	s_nop 1
	v_mov_b32_dpp v170, v38 row_ror:8 row_mask:0xf bank_mask:0xf
	v_mov_b32_dpp v171, v39 row_ror:8 row_mask:0xf bank_mask:0xf
	v_mov_b32_dpp v172, v40 row_ror:8 row_mask:0xf bank_mask:0xf
	v_mov_b32_dpp v173, v41 row_ror:8 row_mask:0xf bank_mask:0xf
	v_mov_b32_dpp v174, v30 row_ror:8 row_mask:0xf bank_mask:0xf
	v_mov_b32_dpp v175, v31 row_ror:8 row_mask:0xf bank_mask:0xf
	v_mov_b32_dpp v176, v32 row_ror:8 row_mask:0xf bank_mask:0xf
	v_mov_b32_dpp v177, v33 row_ror:8 row_mask:0xf bank_mask:0xf
	v_lshl_add_u64 v[250:251], v[76:77], 0, v[254:255]
	v_cndmask_b32_e64 v242, v174, v38, s[98:99]
	v_cndmask_b32_e64 v243, v175, v39, s[98:99]
	v_cndmask_b32_e64 v244, v176, v40, s[98:99]
	v_cndmask_b32_e64 v245, v177, v41, s[98:99]
	v_cndmask_b32_e64 v246, v30, v170, s[98:99]
	v_cndmask_b32_e64 v247, v31, v171, s[98:99]
	v_cndmask_b32_e64 v248, v32, v172, s[98:99]
	v_cndmask_b32_e64 v249, v33, v173, s[98:99]
	v_lshl_add_u64 v[252:253], v[250:251], 0, s[100:101]
	global_store_dwordx4 v[250:251], v[242:245], off offset:512 sc1
	global_store_dwordx4 v[252:253], v[246:249], off offset:512 sc1
	v_pk_mul_f32 v[34:35], v[34:35], v[92:93] op_sel:[0,1]
	v_pk_mul_f32 v[36:37], v[36:37], v[92:93] op_sel:[0,1]
	v_pk_mul_f32 v[26:27], v[26:27], v[92:93] op_sel:[0,1]
	v_pk_mul_f32 v[28:29], v[28:29], v[92:93] op_sel:[0,1]
	v_pk_mul_f32 v[22:23], v[22:23], v[92:93] op_sel:[0,1]
	v_pk_mul_f32 v[24:25], v[24:25], v[92:93] op_sel:[0,1]
	v_pk_mul_f32 v[14:15], v[14:15], v[92:93] op_sel:[0,1]
	v_pk_mul_f32 v[16:17], v[16:17], v[92:93] op_sel:[0,1]
	s_waitcnt vmcnt(15)
	v_pk_fma_f32 v[34:35], v[142:143], v[34:35], v[178:179]
	v_pk_fma_f32 v[36:37], v[144:145], v[36:37], v[180:181]
	v_cndmask_b32_e32 v34, v34, v126, vcc
	v_cndmask_b32_e32 v35, v35, v126, vcc
	v_cndmask_b32_e32 v36, v36, v126, vcc
	v_cndmask_b32_e32 v37, v37, v126, vcc
	s_waitcnt vmcnt(14)
	v_pk_fma_f32 v[26:27], v[138:139], v[26:27], v[182:183]
	v_pk_fma_f32 v[28:29], v[140:141], v[28:29], v[184:185]
	v_cndmask_b32_e32 v26, v26, v126, vcc
	v_cndmask_b32_e32 v27, v27, v126, vcc
	v_cndmask_b32_e32 v28, v28, v126, vcc
	v_cndmask_b32_e32 v29, v29, v126, vcc
	s_nop 1
	v_mov_b32_dpp v178, v34 row_ror:8 row_mask:0xf bank_mask:0xf
	v_mov_b32_dpp v179, v35 row_ror:8 row_mask:0xf bank_mask:0xf
	v_mov_b32_dpp v180, v36 row_ror:8 row_mask:0xf bank_mask:0xf
	v_mov_b32_dpp v181, v37 row_ror:8 row_mask:0xf bank_mask:0xf
	v_mov_b32_dpp v182, v26 row_ror:8 row_mask:0xf bank_mask:0xf
	v_mov_b32_dpp v183, v27 row_ror:8 row_mask:0xf bank_mask:0xf
	v_mov_b32_dpp v184, v28 row_ror:8 row_mask:0xf bank_mask:0xf
	v_mov_b32_dpp v185, v29 row_ror:8 row_mask:0xf bank_mask:0xf
	v_lshl_add_u64 v[250:251], v[80:81], 0, v[254:255]
	v_cndmask_b32_e64 v242, v182, v34, s[98:99]
	v_cndmask_b32_e64 v243, v183, v35, s[98:99]
	v_cndmask_b32_e64 v244, v184, v36, s[98:99]
	v_cndmask_b32_e64 v245, v185, v37, s[98:99]
	v_cndmask_b32_e64 v246, v26, v178, s[98:99]
	v_cndmask_b32_e64 v247, v27, v179, s[98:99]
	v_cndmask_b32_e64 v248, v28, v180, s[98:99]
	v_cndmask_b32_e64 v249, v29, v181, s[98:99]
	v_lshl_add_u64 v[252:253], v[250:251], 0, s[100:101]
	global_store_dwordx4 v[250:251], v[242:245], off sc1
	global_store_dwordx4 v[252:253], v[246:249], off sc1
	s_waitcnt vmcnt(15)
	v_pk_fma_f32 v[22:23], v[134:135], v[22:23], v[186:187]
	v_pk_fma_f32 v[24:25], v[136:137], v[24:25], v[188:189]
	v_cndmask_b32_e32 v22, v22, v126, vcc
	v_cndmask_b32_e32 v23, v23, v126, vcc
	v_cndmask_b32_e32 v24, v24, v126, vcc
	v_cndmask_b32_e32 v25, v25, v126, vcc
	s_waitcnt vmcnt(14)
;     __device__ __forceinline__ void fused(f32x4 (&acc)[2][2][4][2], const Unit& u, int wr, int wc, int fr, int fq, PG8_LAS unsigned char* lds, int wid, int lane) const {
;     ...
;             for (int m = 0; m < 4; ++m) { const int r = ai * HALF + wr * 64 + m * 16 + fr; const f32x2v sr = S[r]; const size_t off = (size_t)(u.pm * BM + r) * ldc + col0;
; #pragma unroll
;                 for (int bj = 0; bj < 2; ++bj)
; #pragma unroll
;                     for (int n = 0; n < 2; ++n) { const f32x4 bs = ai == 0 ? pre[m][bj][n] : *(const f32x4*)(base + off + bj * HALF + n * 16); f32x4 o = bs + cvv[bj][n] * (acc[ai][bj][m][n] * sr.y);
;                         if (bad) o = (f32x4){qnan, qnan, qnan, qnan}; *(f32x4*)(out + off + bj * HALF + n * 16) = o; }
;                 if (m & 1) asm volatile("" ::: "memory"); }
	v_pk_fma_f32 v[14:15], v[130:131], v[14:15], v[190:191]
	v_pk_fma_f32 v[16:17], v[132:133], v[16:17], v[192:193]
	v_cndmask_b32_e32 v14, v14, v126, vcc
	v_cndmask_b32_e32 v15, v15, v126, vcc
	v_cndmask_b32_e32 v16, v16, v126, vcc
	v_cndmask_b32_e32 v17, v17, v126, vcc
	s_nop 1
	v_mov_b32_dpp v186, v22 row_ror:8 row_mask:0xf bank_mask:0xf
	v_mov_b32_dpp v187, v23 row_ror:8 row_mask:0xf bank_mask:0xf
	v_mov_b32_dpp v188, v24 row_ror:8 row_mask:0xf bank_mask:0xf
	v_mov_b32_dpp v189, v25 row_ror:8 row_mask:0xf bank_mask:0xf
	v_mov_b32_dpp v190, v14 row_ror:8 row_mask:0xf bank_mask:0xf
	v_mov_b32_dpp v191, v15 row_ror:8 row_mask:0xf bank_mask:0xf
	v_mov_b32_dpp v192, v16 row_ror:8 row_mask:0xf bank_mask:0xf
	v_mov_b32_dpp v193, v17 row_ror:8 row_mask:0xf bank_mask:0xf
	v_lshl_add_u64 v[250:251], v[80:81], 0, v[254:255]
	v_cndmask_b32_e64 v242, v190, v22, s[98:99]
	v_cndmask_b32_e64 v243, v191, v23, s[98:99]
	v_cndmask_b32_e64 v244, v192, v24, s[98:99]
	v_cndmask_b32_e64 v245, v193, v25, s[98:99]
	v_cndmask_b32_e64 v246, v14, v186, s[98:99]
	v_cndmask_b32_e64 v247, v15, v187, s[98:99]
	v_cndmask_b32_e64 v248, v16, v188, s[98:99]
	v_cndmask_b32_e64 v249, v17, v189, s[98:99]
	v_lshl_add_u64 v[252:253], v[250:251], 0, s[100:101]
	global_store_dwordx4 v[250:251], v[242:245], off offset:512 sc1
	global_store_dwordx4 v[252:253], v[246:249], off offset:512 sc1
	v_pk_mul_f32 v[18:19], v[18:19], v[94:95] op_sel:[0,1]
	v_pk_mul_f32 v[20:21], v[20:21], v[94:95] op_sel:[0,1]
	v_pk_mul_f32 v[10:11], v[10:11], v[94:95] op_sel:[0,1]
	v_pk_mul_f32 v[12:13], v[12:13], v[94:95] op_sel:[0,1]
	v_pk_mul_f32 v[6:7], v[6:7], v[94:95] op_sel:[0,1]
	v_pk_mul_f32 v[8:9], v[8:9], v[94:95] op_sel:[0,1]
	v_pk_mul_f32 v[2:3], v[2:3], v[94:95] op_sel:[0,1]
	v_pk_mul_f32 v[4:5], v[4:5], v[94:95] op_sel:[0,1]
	s_waitcnt vmcnt(15)
	v_pk_fma_f32 v[18:19], v[142:143], v[18:19], v[194:195]
	v_pk_fma_f32 v[20:21], v[144:145], v[20:21], v[196:197]
	v_cndmask_b32_e32 v18, v18, v126, vcc
	v_cndmask_b32_e32 v19, v19, v126, vcc
	v_cndmask_b32_e32 v20, v20, v126, vcc
	v_cndmask_b32_e32 v21, v21, v126, vcc
	s_waitcnt vmcnt(14)
	v_pk_fma_f32 v[10:11], v[138:139], v[10:11], v[198:199]
	v_pk_fma_f32 v[12:13], v[140:141], v[12:13], v[200:201]
	v_cndmask_b32_e32 v10, v10, v126, vcc
	v_cndmask_b32_e32 v11, v11, v126, vcc
	v_cndmask_b32_e32 v12, v12, v126, vcc
	v_cndmask_b32_e32 v13, v13, v126, vcc
	s_nop 1
	v_mov_b32_dpp v194, v18 row_ror:8 row_mask:0xf bank_mask:0xf
	v_mov_b32_dpp v195, v19 row_ror:8 row_mask:0xf bank_mask:0xf
	v_mov_b32_dpp v196, v20 row_ror:8 row_mask:0xf bank_mask:0xf
	v_mov_b32_dpp v197, v21 row_ror:8 row_mask:0xf bank_mask:0xf
	v_mov_b32_dpp v198, v10 row_ror:8 row_mask:0xf bank_mask:0xf
	v_mov_b32_dpp v199, v11 row_ror:8 row_mask:0xf bank_mask:0xf
	v_mov_b32_dpp v200, v12 row_ror:8 row_mask:0xf bank_mask:0xf
	v_mov_b32_dpp v201, v13 row_ror:8 row_mask:0xf bank_mask:0xf
	v_lshl_add_u64 v[250:251], v[84:85], 0, v[254:255]
	v_cndmask_b32_e64 v242, v198, v18, s[98:99]
	v_cndmask_b32_e64 v243, v199, v19, s[98:99]
	v_cndmask_b32_e64 v244, v200, v20, s[98:99]
	v_cndmask_b32_e64 v245, v201, v21, s[98:99]
	v_cndmask_b32_e64 v246, v10, v194, s[98:99]
	v_cndmask_b32_e64 v247, v11, v195, s[98:99]
	v_cndmask_b32_e64 v248, v12, v196, s[98:99]
	v_cndmask_b32_e64 v249, v13, v197, s[98:99]
	v_lshl_add_u64 v[252:253], v[250:251], 0, s[100:101]
	global_store_dwordx4 v[250:251], v[242:245], off sc1
	global_store_dwordx4 v[252:253], v[246:249], off sc1
	s_waitcnt vmcnt(15)
	v_pk_fma_f32 v[6:7], v[134:135], v[6:7], v[202:203]
	v_pk_fma_f32 v[8:9], v[136:137], v[8:9], v[204:205]
	v_cndmask_b32_e32 v6, v6, v126, vcc
	v_cndmask_b32_e32 v7, v7, v126, vcc
	v_cndmask_b32_e32 v8, v8, v126, vcc
	v_cndmask_b32_e32 v9, v9, v126, vcc
	s_waitcnt vmcnt(14)
	v_pk_fma_f32 v[2:3], v[130:131], v[2:3], v[206:207]
	v_pk_fma_f32 v[4:5], v[132:133], v[4:5], v[208:209]
	v_cndmask_b32_e32 v2, v2, v126, vcc
	v_cndmask_b32_e32 v3, v3, v126, vcc
	v_cndmask_b32_e32 v4, v4, v126, vcc
	v_cndmask_b32_e32 v5, v5, v126, vcc
	s_nop 1
	v_mov_b32_dpp v202, v6 row_ror:8 row_mask:0xf bank_mask:0xf
	v_mov_b32_dpp v203, v7 row_ror:8 row_mask:0xf bank_mask:0xf
	v_mov_b32_dpp v204, v8 row_ror:8 row_mask:0xf bank_mask:0xf
	v_mov_b32_dpp v205, v9 row_ror:8 row_mask:0xf bank_mask:0xf
	v_mov_b32_dpp v206, v2 row_ror:8 row_mask:0xf bank_mask:0xf
	v_mov_b32_dpp v207, v3 row_ror:8 row_mask:0xf bank_mask:0xf
	v_mov_b32_dpp v208, v4 row_ror:8 row_mask:0xf bank_mask:0xf
	v_mov_b32_dpp v209, v5 row_ror:8 row_mask:0xf bank_mask:0xf
	v_lshl_add_u64 v[250:251], v[84:85], 0, v[254:255]
	v_cndmask_b32_e64 v242, v206, v6, s[98:99]
	v_cndmask_b32_e64 v243, v207, v7, s[98:99]
	v_cndmask_b32_e64 v244, v208, v8, s[98:99]
	v_cndmask_b32_e64 v245, v209, v9, s[98:99]
	v_cndmask_b32_e64 v246, v2, v202, s[98:99]
	v_cndmask_b32_e64 v247, v3, v203, s[98:99]
	v_cndmask_b32_e64 v248, v4, v204, s[98:99]
	v_cndmask_b32_e64 v249, v5, v205, s[98:99]
	v_lshl_add_u64 v[252:253], v[250:251], 0, s[100:101]
	global_store_dwordx4 v[250:251], v[242:245], off offset:512 sc1
	global_store_dwordx4 v[252:253], v[246:249], off offset:512 sc1

; __global__ void __launch_bounds__(NT, 2) fwd_kernel(Args args) {
	.amdhsa_kernel _Z10fwd_kernel4Args
		.amdhsa_group_segment_fixed_size 0
		.amdhsa_private_segment_fixed_size 0
		.amdhsa_kernarg_size 496
		.amdhsa_user_sgpr_count 2
		.amdhsa_user_sgpr_dispatch_ptr 0
		.amdhsa_user_sgpr_queue_ptr 0
		.amdhsa_user_sgpr_kernarg_segment_ptr 1
		.amdhsa_user_sgpr_dispatch_id 0
		.amdhsa_user_sgpr_kernarg_preload_length 0
		.amdhsa_user_sgpr_kernarg_preload_offset 0
		.amdhsa_user_sgpr_private_segment_size 0
		.amdhsa_uses_dynamic_stack 0
		.amdhsa_enable_private_segment 0
		.amdhsa_system_sgpr_workgroup_id_x 1
		.amdhsa_system_sgpr_workgroup_id_y 0
		.amdhsa_system_sgpr_workgroup_id_z 0
		.amdhsa_system_sgpr_workgroup_info 0
		.amdhsa_system_vgpr_workitem_id 0
		.amdhsa_next_free_vgpr 256
		.amdhsa_next_free_sgpr 102
		.amdhsa_accum_offset 256
		.amdhsa_reserve_vcc 1
		.amdhsa_float_round_mode_32 0
		.amdhsa_float_round_mode_16_64 0
		.amdhsa_float_denorm_mode_32 3
		.amdhsa_float_denorm_mode_16_64 3
		.amdhsa_dx10_clamp 1
		.amdhsa_ieee_mode 1
		.amdhsa_fp16_overflow 0
		.amdhsa_tg_split 0
		.amdhsa_exception_fp_ieee_invalid_op 0
		.amdhsa_exception_fp_denorm_src 0
		.amdhsa_exception_fp_ieee_div_zero 0
		.amdhsa_exception_fp_ieee_overflow 0
		.amdhsa_exception_fp_ieee_underflow 0
		.amdhsa_exception_fp_ieee_inexact 0
		.amdhsa_exception_int_div_zero 0
	.end_amdhsa_kernel

; __global__ void __launch_bounds__(NT, 2) fwd_kernel(Args args) {
amdhsa.kernels:
  - .agpr_count:     0
    .args:
      - .offset:         0
        .size:           240
        .value_kind:     by_value
      - .offset:         240
        .size:           4
        .value_kind:     hidden_block_count_x
      - .offset:         244
        .size:           4
        .value_kind:     hidden_block_count_y
      - .offset:         248
        .size:           4
        .value_kind:     hidden_block_count_z
      - .offset:         252
        .size:           2
        .value_kind:     hidden_group_size_x
      - .offset:         254
        .size:           2
        .value_kind:     hidden_group_size_y
      - .offset:         256
        .size:           2
        .value_kind:     hidden_group_size_z
      - .offset:         258
        .size:           2
        .value_kind:     hidden_remainder_x
      - .offset:         260
        .size:           2
        .value_kind:     hidden_remainder_y
      - .offset:         262
        .size:           2
        .value_kind:     hidden_remainder_z
      - .offset:         280
        .size:           8
        .value_kind:     hidden_global_offset_x
      - .offset:         288
        .size:           8
        .value_kind:     hidden_global_offset_y
      - .offset:         296
        .size:           8
        .value_kind:     hidden_global_offset_z
      - .offset:         304
        .size:           2
        .value_kind:     hidden_grid_dims
      - .offset:         360
        .size:           4
        .value_kind:     hidden_dynamic_lds_size
    .group_segment_fixed_size: 0
    .kernarg_segment_align: 8
    .kernarg_segment_size: 496
    .language:       OpenCL C
    .language_version:
      - 2
      - 0
    .max_flat_workgroup_size: 512
    .name:           _Z10fwd_kernel4Args
    .private_segment_fixed_size: 0
    .sgpr_count:     108
    .sgpr_spill_count: 36
    .symbol:         _Z10fwd_kernel4Args.kd
    .uniform_work_group_size: 1
    .uses_dynamic_stack: false
    .vgpr_count:     256
    .vgpr_spill_count: 0
    .wavefront_size: 64
